# MFMA-opening barrier after 4 MFMAs in super-phases 1/3 and after 2 MFMAs in super-phases 2/4
# speedup vs baseline: 1.0018x; 1.0018x over previous
.LBB0_233:
	ds_read_b128 v[130:133], v213
	ds_read_b128 v[134:137], v214
	ds_read_b128 v[138:141], v215
	ds_read_b128 v[142:145], v216
	ds_read_b128 v[146:149], v217
	ds_read_b128 v[150:153], v218
	ds_read_b128 v[154:157], v219
	ds_read_b128 v[158:161], v220
	s_add_i32 s4, s33, 0xffffe080
	s_cmp_eq_u32 s58, 12
	s_cselect_b32 s61, s18, s4
	s_cselect_b32 s60, s19, s57
	s_add_i32 s59, s61, 0x80
	s_mov_b32 s4, s70
	s_mov_b32 m0, s38
	ds_read_b128 v[162:165], v221
	ds_read_b128 v[166:169], v221 offset:2048
	ds_read_b128 v[170:173], v222
	ds_read_b128 v[174:177], v222 offset:2048
	ds_read_b128 v[178:181], v221 offset:4096
	ds_read_b128 v[182:185], v221 offset:6144
	ds_read_b128 v[186:189], v222 offset:4096
	ds_read_b128 v[190:193], v222 offset:6144
	buffer_load_dwordx4 v207, s[4:7], s33 offen lds
	s_mov_b32 m0, s41
	s_nop 0
	buffer_load_dwordx4 v209, s[4:7], s33 offen lds
	s_waitcnt vmcnt(8)
	s_waitcnt lgkmcnt(0)
	s_setprio 1
	v_mfma_f32_16x16x32_bf16 v[114:117], v[130:133], v[162:165], v[114:117]
	v_mfma_f32_16x16x32_bf16 v[110:113], v[138:141], v[162:165], v[110:113]
	v_mfma_f32_16x16x32_bf16 v[106:109], v[130:133], v[166:169], v[106:109]
	v_mfma_f32_16x16x32_bf16 v[102:105], v[138:141], v[166:169], v[102:105]
	s_barrier
	v_mfma_f32_16x16x32_bf16 v[98:101], v[130:133], v[178:181], v[98:101]
	v_mfma_f32_16x16x32_bf16 v[94:97], v[138:141], v[178:181], v[94:97]
	v_mfma_f32_16x16x32_bf16 v[90:93], v[130:133], v[182:185], v[90:93]
	v_mfma_f32_16x16x32_bf16 v[86:89], v[138:141], v[182:185], v[86:89]
	v_mfma_f32_16x16x32_bf16 v[114:117], v[134:137], v[170:173], v[114:117]
	v_mfma_f32_16x16x32_bf16 v[110:113], v[142:145], v[170:173], v[110:113]
	v_mfma_f32_16x16x32_bf16 v[106:109], v[134:137], v[174:177], v[106:109]
	v_mfma_f32_16x16x32_bf16 v[102:105], v[142:145], v[174:177], v[102:105]
	v_mfma_f32_16x16x32_bf16 v[98:101], v[134:137], v[186:189], v[98:101]
	v_mfma_f32_16x16x32_bf16 v[94:97], v[142:145], v[186:189], v[94:97]
	v_mfma_f32_16x16x32_bf16 v[90:93], v[134:137], v[190:193], v[90:93]
	v_mfma_f32_16x16x32_bf16 v[86:89], v[142:145], v[190:193], v[86:89]
	v_mfma_f32_16x16x32_bf16 v[82:85], v[146:149], v[162:165], v[82:85]
	v_mfma_f32_16x16x32_bf16 v[74:77], v[154:157], v[162:165], v[74:77]
	v_mfma_f32_16x16x32_bf16 v[70:73], v[146:149], v[166:169], v[70:73]
	v_mfma_f32_16x16x32_bf16 v[66:69], v[154:157], v[166:169], v[66:69]
	v_mfma_f32_16x16x32_bf16 v[62:65], v[146:149], v[178:181], v[62:65]
	v_mfma_f32_16x16x32_bf16 v[58:61], v[154:157], v[178:181], v[58:61]
	v_mfma_f32_16x16x32_bf16 v[54:57], v[146:149], v[182:185], v[54:57]
	v_mfma_f32_16x16x32_bf16 v[50:53], v[154:157], v[182:185], v[50:53]
	v_mfma_f32_16x16x32_bf16 v[82:85], v[150:153], v[170:173], v[82:85]
	v_mfma_f32_16x16x32_bf16 v[74:77], v[158:161], v[170:173], v[74:77]
	v_mfma_f32_16x16x32_bf16 v[70:73], v[150:153], v[174:177], v[70:73]
	v_mfma_f32_16x16x32_bf16 v[66:69], v[158:161], v[174:177], v[66:69]
	v_mfma_f32_16x16x32_bf16 v[62:65], v[150:153], v[186:189], v[62:65]
	v_mfma_f32_16x16x32_bf16 v[58:61], v[158:161], v[186:189], v[58:61]
	v_mfma_f32_16x16x32_bf16 v[54:57], v[150:153], v[190:193], v[54:57]
	v_mfma_f32_16x16x32_bf16 v[50:53], v[158:161], v[190:193], v[50:53]
	s_barrier
	s_setprio 0
	s_mov_b32 m0, s21
	ds_read_b128 v[162:165], v221 offset:16384
	ds_read_b128 v[166:169], v221 offset:18432
	ds_read_b128 v[170:173], v222 offset:16384
	ds_read_b128 v[174:177], v222 offset:18432
	ds_read_b128 v[178:181], v221 offset:20480
	ds_read_b128 v[182:185], v221 offset:22528
	ds_read_b128 v[186:189], v222 offset:20480
	ds_read_b128 v[190:193], v222 offset:22528
	buffer_load_dwordx4 v208, s[4:7], s60 offen lds
	s_mov_b32 m0, s22
	s_add_i32 s62, s60, 0x40000
	buffer_load_dwordx4 v210, s[4:7], s60 offen lds
	s_mov_b32 m0, s23
	s_nop 0
	buffer_load_dwordx4 v208, s[4:7], s62 offen lds
	s_mov_b32 m0, s24
	s_nop 0
	buffer_load_dwordx4 v210, s[4:7], s62 offen lds
	s_mov_b32 m0, s20
	s_nop 0
	buffer_load_dwordx4 v207, s[4:7], s61 offen lds
	s_mov_b32 m0, s25
	s_nop 0
	buffer_load_dwordx4 v209, s[4:7], s61 offen lds
	s_waitcnt vmcnt(8)
	s_waitcnt lgkmcnt(0)
	s_setprio 1
	v_mfma_f32_16x16x32_bf16 v[78:81], v[130:133], v[162:165], v[78:81]
	v_mfma_f32_16x16x32_bf16 v[46:49], v[138:141], v[162:165], v[46:49]
	s_barrier
	v_mfma_f32_16x16x32_bf16 v[42:45], v[130:133], v[166:169], v[42:45]
	v_mfma_f32_16x16x32_bf16 v[38:41], v[138:141], v[166:169], v[38:41]
	v_mfma_f32_16x16x32_bf16 v[34:37], v[130:133], v[178:181], v[34:37]
	v_mfma_f32_16x16x32_bf16 v[30:33], v[138:141], v[178:181], v[30:33]
	v_mfma_f32_16x16x32_bf16 v[26:29], v[130:133], v[182:185], v[26:29]
	v_mfma_f32_16x16x32_bf16 v[22:25], v[138:141], v[182:185], v[22:25]
	v_mfma_f32_16x16x32_bf16 v[78:81], v[134:137], v[170:173], v[78:81]
	v_mfma_f32_16x16x32_bf16 v[46:49], v[142:145], v[170:173], v[46:49]
	v_mfma_f32_16x16x32_bf16 v[42:45], v[134:137], v[174:177], v[42:45]
	v_mfma_f32_16x16x32_bf16 v[38:41], v[142:145], v[174:177], v[38:41]
	v_mfma_f32_16x16x32_bf16 v[34:37], v[134:137], v[186:189], v[34:37]
	v_mfma_f32_16x16x32_bf16 v[30:33], v[142:145], v[186:189], v[30:33]
	v_mfma_f32_16x16x32_bf16 v[26:29], v[134:137], v[190:193], v[26:29]
	v_mfma_f32_16x16x32_bf16 v[22:25], v[142:145], v[190:193], v[22:25]
	v_mfma_f32_16x16x32_bf16 v[18:21], v[146:149], v[162:165], v[18:21]
	v_mfma_f32_16x16x32_bf16 v[14:17], v[154:157], v[162:165], v[14:17]
	v_mfma_f32_16x16x32_bf16 v[10:13], v[146:149], v[166:169], v[10:13]
	v_mfma_f32_16x16x32_bf16 v[6:9], v[154:157], v[166:169], v[6:9]
	v_mfma_f32_16x16x32_bf16 v[2:5], v[146:149], v[178:181], v[2:5]
	v_mfma_f32_16x16x32_bf16 v[126:129], v[154:157], v[178:181], v[126:129]
	v_mfma_f32_16x16x32_bf16 v[122:125], v[146:149], v[182:185], v[122:125]
	v_mfma_f32_16x16x32_bf16 v[118:121], v[154:157], v[182:185], v[118:121]
	v_mfma_f32_16x16x32_bf16 v[18:21], v[150:153], v[170:173], v[18:21]
	v_mfma_f32_16x16x32_bf16 v[14:17], v[158:161], v[170:173], v[14:17]
	v_mfma_f32_16x16x32_bf16 v[10:13], v[150:153], v[174:177], v[10:13]
	v_mfma_f32_16x16x32_bf16 v[6:9], v[158:161], v[174:177], v[6:9]
	v_mfma_f32_16x16x32_bf16 v[2:5], v[150:153], v[186:189], v[2:5]
	v_mfma_f32_16x16x32_bf16 v[126:129], v[158:161], v[186:189], v[126:129]
	v_mfma_f32_16x16x32_bf16 v[122:125], v[150:153], v[190:193], v[122:125]
	v_mfma_f32_16x16x32_bf16 v[118:121], v[158:161], v[190:193], v[118:121]
	s_barrier
	s_setprio 0
	ds_read_b128 v[130:133], v194
	ds_read_b128 v[134:137], v224
	ds_read_b128 v[138:141], v225
	ds_read_b128 v[142:145], v228
	ds_read_b128 v[146:149], v229
	ds_read_b128 v[150:153], v230
	ds_read_b128 v[154:157], v231
	ds_read_b128 v[158:161], v233
	s_addk_i32 s61, 0x2000
	s_mov_b32 m0, s26
	ds_read_b128 v[162:165], v221 offset:32768
	ds_read_b128 v[166:169], v221 offset:34816
	ds_read_b128 v[170:173], v222 offset:32768
	ds_read_b128 v[174:177], v222 offset:34816
	ds_read_b128 v[178:181], v221 offset:36864
	ds_read_b128 v[182:185], v221 offset:38912
	ds_read_b128 v[186:189], v222 offset:36864
	ds_read_b128 v[190:193], v222 offset:38912
	buffer_load_dwordx4 v207, s[4:7], s61 offen lds
	s_mov_b32 m0, s27
	s_nop 0
	buffer_load_dwordx4 v209, s[4:7], s61 offen lds
	s_waitcnt vmcnt(8)
	s_waitcnt lgkmcnt(0)
	s_setprio 1
	v_mfma_f32_16x16x32_bf16 v[114:117], v[130:133], v[162:165], v[114:117]
	v_mfma_f32_16x16x32_bf16 v[110:113], v[138:141], v[162:165], v[110:113]
	v_mfma_f32_16x16x32_bf16 v[106:109], v[130:133], v[166:169], v[106:109]
	v_mfma_f32_16x16x32_bf16 v[102:105], v[138:141], v[166:169], v[102:105]
	s_barrier
	v_mfma_f32_16x16x32_bf16 v[98:101], v[130:133], v[178:181], v[98:101]
	v_mfma_f32_16x16x32_bf16 v[94:97], v[138:141], v[178:181], v[94:97]
	v_mfma_f32_16x16x32_bf16 v[90:93], v[130:133], v[182:185], v[90:93]
	v_mfma_f32_16x16x32_bf16 v[86:89], v[138:141], v[182:185], v[86:89]
	v_mfma_f32_16x16x32_bf16 v[114:117], v[134:137], v[170:173], v[114:117]
	v_mfma_f32_16x16x32_bf16 v[110:113], v[142:145], v[170:173], v[110:113]
	v_mfma_f32_16x16x32_bf16 v[106:109], v[134:137], v[174:177], v[106:109]
	v_mfma_f32_16x16x32_bf16 v[102:105], v[142:145], v[174:177], v[102:105]
	v_mfma_f32_16x16x32_bf16 v[98:101], v[134:137], v[186:189], v[98:101]
	v_mfma_f32_16x16x32_bf16 v[94:97], v[142:145], v[186:189], v[94:97]
	v_mfma_f32_16x16x32_bf16 v[90:93], v[134:137], v[190:193], v[90:93]
	v_mfma_f32_16x16x32_bf16 v[86:89], v[142:145], v[190:193], v[86:89]
	v_mfma_f32_16x16x32_bf16 v[82:85], v[146:149], v[162:165], v[82:85]
	v_mfma_f32_16x16x32_bf16 v[74:77], v[154:157], v[162:165], v[74:77]
	v_mfma_f32_16x16x32_bf16 v[70:73], v[146:149], v[166:169], v[70:73]
	v_mfma_f32_16x16x32_bf16 v[66:69], v[154:157], v[166:169], v[66:69]
	v_mfma_f32_16x16x32_bf16 v[62:65], v[146:149], v[178:181], v[62:65]
	v_mfma_f32_16x16x32_bf16 v[58:61], v[154:157], v[178:181], v[58:61]
	v_mfma_f32_16x16x32_bf16 v[54:57], v[146:149], v[182:185], v[54:57]
	v_mfma_f32_16x16x32_bf16 v[50:53], v[154:157], v[182:185], v[50:53]
	v_mfma_f32_16x16x32_bf16 v[82:85], v[150:153], v[170:173], v[82:85]
	v_mfma_f32_16x16x32_bf16 v[74:77], v[158:161], v[170:173], v[74:77]
	v_mfma_f32_16x16x32_bf16 v[70:73], v[150:153], v[174:177], v[70:73]
	v_mfma_f32_16x16x32_bf16 v[66:69], v[158:161], v[174:177], v[66:69]
	v_mfma_f32_16x16x32_bf16 v[62:65], v[150:153], v[186:189], v[62:65]
	v_mfma_f32_16x16x32_bf16 v[58:61], v[158:161], v[186:189], v[58:61]
	v_mfma_f32_16x16x32_bf16 v[54:57], v[150:153], v[190:193], v[54:57]
	v_mfma_f32_16x16x32_bf16 v[50:53], v[158:161], v[190:193], v[50:53]
	s_barrier
	s_setprio 0
	s_mov_b32 m0, s29
	s_add_i32 s61, s60, 0x80
	ds_read_b128 v[162:165], v221 offset:49152
	ds_read_b128 v[166:169], v221 offset:51200
	ds_read_b128 v[170:173], v222 offset:49152
	ds_read_b128 v[174:177], v222 offset:51200
	ds_read_b128 v[178:181], v221 offset:53248
	ds_read_b128 v[182:185], v221 offset:55296
	ds_read_b128 v[186:189], v222 offset:53248
	ds_read_b128 v[190:193], v222 offset:55296
	buffer_load_dwordx4 v208, s[4:7], s61 offen lds
	s_mov_b32 m0, s30
	s_add_i32 s60, s60, 0x40080
	buffer_load_dwordx4 v210, s[4:7], s61 offen lds
	s_mov_b32 m0, s35
	s_nop 0
	buffer_load_dwordx4 v208, s[4:7], s60 offen lds
	s_mov_b32 m0, s36
	s_nop 0
	buffer_load_dwordx4 v210, s[4:7], s60 offen lds
	s_mov_b32 m0, s31
	s_nop 0
	buffer_load_dwordx4 v207, s[4:7], s59 offen lds
	s_mov_b32 m0, s34
	s_nop 0
	buffer_load_dwordx4 v209, s[4:7], s59 offen lds
	s_waitcnt vmcnt(8)
	s_waitcnt lgkmcnt(0)
	s_setprio 1
	v_mfma_f32_16x16x32_bf16 v[78:81], v[130:133], v[162:165], v[78:81]
	v_mfma_f32_16x16x32_bf16 v[46:49], v[138:141], v[162:165], v[46:49]
	s_barrier
	v_mfma_f32_16x16x32_bf16 v[42:45], v[130:133], v[166:169], v[42:45]
	v_mfma_f32_16x16x32_bf16 v[38:41], v[138:141], v[166:169], v[38:41]
	v_mfma_f32_16x16x32_bf16 v[34:37], v[130:133], v[178:181], v[34:37]
	v_mfma_f32_16x16x32_bf16 v[30:33], v[138:141], v[178:181], v[30:33]
	v_mfma_f32_16x16x32_bf16 v[26:29], v[130:133], v[182:185], v[26:29]
	v_mfma_f32_16x16x32_bf16 v[22:25], v[138:141], v[182:185], v[22:25]
	v_mfma_f32_16x16x32_bf16 v[78:81], v[134:137], v[170:173], v[78:81]
	v_mfma_f32_16x16x32_bf16 v[46:49], v[142:145], v[170:173], v[46:49]
	v_mfma_f32_16x16x32_bf16 v[42:45], v[134:137], v[174:177], v[42:45]
	v_mfma_f32_16x16x32_bf16 v[38:41], v[142:145], v[174:177], v[38:41]
	v_mfma_f32_16x16x32_bf16 v[34:37], v[134:137], v[186:189], v[34:37]
	v_mfma_f32_16x16x32_bf16 v[30:33], v[142:145], v[186:189], v[30:33]
	v_mfma_f32_16x16x32_bf16 v[26:29], v[134:137], v[190:193], v[26:29]
	v_mfma_f32_16x16x32_bf16 v[22:25], v[142:145], v[190:193], v[22:25]
	v_mfma_f32_16x16x32_bf16 v[18:21], v[146:149], v[162:165], v[18:21]
	v_mfma_f32_16x16x32_bf16 v[14:17], v[154:157], v[162:165], v[14:17]
	v_mfma_f32_16x16x32_bf16 v[10:13], v[146:149], v[166:169], v[10:13]
	v_mfma_f32_16x16x32_bf16 v[6:9], v[154:157], v[166:169], v[6:9]
	v_mfma_f32_16x16x32_bf16 v[2:5], v[146:149], v[178:181], v[2:5]
	v_mfma_f32_16x16x32_bf16 v[126:129], v[154:157], v[178:181], v[126:129]
	v_mfma_f32_16x16x32_bf16 v[122:125], v[146:149], v[182:185], v[122:125]
	v_mfma_f32_16x16x32_bf16 v[118:121], v[154:157], v[182:185], v[118:121]
	v_mfma_f32_16x16x32_bf16 v[18:21], v[150:153], v[170:173], v[18:21]
	v_mfma_f32_16x16x32_bf16 v[14:17], v[158:161], v[170:173], v[14:17]
	v_mfma_f32_16x16x32_bf16 v[10:13], v[150:153], v[174:177], v[10:13]
	v_mfma_f32_16x16x32_bf16 v[6:9], v[158:161], v[174:177], v[6:9]
	v_mfma_f32_16x16x32_bf16 v[2:5], v[150:153], v[186:189], v[2:5]
	v_mfma_f32_16x16x32_bf16 v[126:129], v[158:161], v[186:189], v[126:129]
	v_mfma_f32_16x16x32_bf16 v[122:125], v[150:153], v[190:193], v[122:125]
	v_mfma_f32_16x16x32_bf16 v[118:121], v[158:161], v[190:193], v[118:121]
	s_barrier
	s_setprio 0
	s_add_i32 s58, s58, 2
	s_addk_i32 s33, 0x100
	s_addk_i32 s57, 0x100
	s_cmp_gt_u32 s58, 13
	s_cbranch_scc0 .LBB0_233
	s_and_b64 vcc, exec, s[16:17]
	s_cbranch_vccz .LBB0_236
	s_barrier

.LBB0_546:
	ds_read_b128 v[130:133], v211
	ds_read_b128 v[134:137], v212
	ds_read_b128 v[138:141], v213
	ds_read_b128 v[142:145], v214
	ds_read_b128 v[146:149], v215
	ds_read_b128 v[150:153], v216
	ds_read_b128 v[154:157], v217
	ds_read_b128 v[158:161], v218
	s_add_i32 s4, s62, 0x80
	s_cmp_eq_u32 s63, s78
	s_cselect_b32 s84, s64, s4
	s_cselect_b32 s82, s33, s59
	s_cselect_b32 s81, s65, s61
	s_cselect_b32 s80, s56, s60
	s_add_i32 s79, s84, 0x80
	s_add_i32 s83, s60, s62
	s_mov_b32 s4, s70
	s_mov_b32 m0, s43
	ds_read_b128 v[162:165], v219
	ds_read_b128 v[166:169], v219 offset:2048
	ds_read_b128 v[170:173], v220
	ds_read_b128 v[174:177], v220 offset:2048
	ds_read_b128 v[178:181], v219 offset:4096
	ds_read_b128 v[182:185], v219 offset:6144
	ds_read_b128 v[186:189], v220 offset:4096
	ds_read_b128 v[190:193], v220 offset:6144
	buffer_load_dwordx4 v194, s[4:7], s83 offen lds
	s_mov_b32 m0, s44
	s_nop 0
	buffer_load_dwordx4 v222, s[4:7], s83 offen lds
	s_waitcnt vmcnt(8)
	s_waitcnt lgkmcnt(0)
	s_setprio 1
	v_mfma_f32_16x16x32_bf16 v[126:129], v[130:133], v[162:165], v[126:129]
	v_mfma_f32_16x16x32_bf16 v[122:125], v[138:141], v[162:165], v[122:125]
	v_mfma_f32_16x16x32_bf16 v[118:121], v[130:133], v[166:169], v[118:121]
	v_mfma_f32_16x16x32_bf16 v[114:117], v[138:141], v[166:169], v[114:117]
	s_barrier
	v_mfma_f32_16x16x32_bf16 v[110:113], v[130:133], v[178:181], v[110:113]
	v_mfma_f32_16x16x32_bf16 v[106:109], v[138:141], v[178:181], v[106:109]
	v_mfma_f32_16x16x32_bf16 v[102:105], v[130:133], v[182:185], v[102:105]
	v_mfma_f32_16x16x32_bf16 v[98:101], v[138:141], v[182:185], v[98:101]
	v_mfma_f32_16x16x32_bf16 v[126:129], v[134:137], v[170:173], v[126:129]
	v_mfma_f32_16x16x32_bf16 v[122:125], v[142:145], v[170:173], v[122:125]
	v_mfma_f32_16x16x32_bf16 v[118:121], v[134:137], v[174:177], v[118:121]
	v_mfma_f32_16x16x32_bf16 v[114:117], v[142:145], v[174:177], v[114:117]
	v_mfma_f32_16x16x32_bf16 v[110:113], v[134:137], v[186:189], v[110:113]
	v_mfma_f32_16x16x32_bf16 v[106:109], v[142:145], v[186:189], v[106:109]
	v_mfma_f32_16x16x32_bf16 v[102:105], v[134:137], v[190:193], v[102:105]
	v_mfma_f32_16x16x32_bf16 v[98:101], v[142:145], v[190:193], v[98:101]
	v_mfma_f32_16x16x32_bf16 v[94:97], v[146:149], v[162:165], v[94:97]
	v_mfma_f32_16x16x32_bf16 v[90:93], v[154:157], v[162:165], v[90:93]
	v_mfma_f32_16x16x32_bf16 v[86:89], v[146:149], v[166:169], v[86:89]
	v_mfma_f32_16x16x32_bf16 v[82:85], v[154:157], v[166:169], v[82:85]
	v_mfma_f32_16x16x32_bf16 v[78:81], v[146:149], v[178:181], v[78:81]
	v_mfma_f32_16x16x32_bf16 v[74:77], v[154:157], v[178:181], v[74:77]
	v_mfma_f32_16x16x32_bf16 v[70:73], v[146:149], v[182:185], v[70:73]
	v_mfma_f32_16x16x32_bf16 v[66:69], v[154:157], v[182:185], v[66:69]
	v_mfma_f32_16x16x32_bf16 v[94:97], v[150:153], v[170:173], v[94:97]
	v_mfma_f32_16x16x32_bf16 v[90:93], v[158:161], v[170:173], v[90:93]
	v_mfma_f32_16x16x32_bf16 v[86:89], v[150:153], v[174:177], v[86:89]
	v_mfma_f32_16x16x32_bf16 v[82:85], v[158:161], v[174:177], v[82:85]
	v_mfma_f32_16x16x32_bf16 v[78:81], v[150:153], v[186:189], v[78:81]
	v_mfma_f32_16x16x32_bf16 v[74:77], v[158:161], v[186:189], v[74:77]
	v_mfma_f32_16x16x32_bf16 v[70:73], v[150:153], v[190:193], v[70:73]
	v_mfma_f32_16x16x32_bf16 v[66:69], v[158:161], v[190:193], v[66:69]
	s_barrier
	s_setprio 0
	s_cmp_eq_u32 s82, 0
	s_cselect_b64 s[82:83], -1, 0
	v_cndmask_b32_e64 v233, v200, 0, s[82:83]
	s_mov_b32 m0, s25
	v_sub_u32_e32 v233, v201, v233
	v_cndmask_b32_e64 v234, v203, 0, s[82:83]
	ds_read_b128 v[162:165], v219 offset:16384
	ds_read_b128 v[166:169], v219 offset:18432
	ds_read_b128 v[170:173], v220 offset:16384
	ds_read_b128 v[174:177], v220 offset:18432
	ds_read_b128 v[178:181], v219 offset:20480
	ds_read_b128 v[182:185], v219 offset:22528
	ds_read_b128 v[186:189], v220 offset:20480
	ds_read_b128 v[190:193], v220 offset:22528
	buffer_load_dwordx4 v233, s[4:7], s81 offen lds
	v_sub_u32_e32 v234, v204, v234
	s_mov_b32 m0, s26
	s_add_i32 s85, s81, s80
	buffer_load_dwordx4 v234, s[4:7], s81 offen lds
	s_mov_b32 m0, s27
	v_cndmask_b32_e64 v235, v205, 0, s[82:83]
	buffer_load_dwordx4 v233, s[4:7], s85 offen lds
	s_mov_b32 m0, s28
	v_sub_u32_e32 v235, v1, v235
	buffer_load_dwordx4 v234, s[4:7], s85 offen lds
	s_mov_b32 m0, s24
	v_cndmask_b32_e64 v236, v206, 0, s[82:83]
	buffer_load_dwordx4 v235, s[4:7], s84 offen lds
	v_sub_u32_e32 v236, v202, v236
	s_mov_b32 m0, s29
	s_nop 0
	buffer_load_dwordx4 v236, s[4:7], s84 offen lds
	s_waitcnt vmcnt(8)
	s_waitcnt lgkmcnt(0)
	s_setprio 1
	v_mfma_f32_16x16x32_bf16 v[62:65], v[130:133], v[162:165], v[62:65]
	v_mfma_f32_16x16x32_bf16 v[58:61], v[138:141], v[162:165], v[58:61]
	s_barrier
	v_mfma_f32_16x16x32_bf16 v[54:57], v[130:133], v[166:169], v[54:57]
	v_mfma_f32_16x16x32_bf16 v[50:53], v[138:141], v[166:169], v[50:53]
	v_mfma_f32_16x16x32_bf16 v[46:49], v[130:133], v[178:181], v[46:49]
	v_mfma_f32_16x16x32_bf16 v[42:45], v[138:141], v[178:181], v[42:45]
	v_mfma_f32_16x16x32_bf16 v[38:41], v[130:133], v[182:185], v[38:41]
	v_mfma_f32_16x16x32_bf16 v[34:37], v[138:141], v[182:185], v[34:37]
	v_mfma_f32_16x16x32_bf16 v[62:65], v[134:137], v[170:173], v[62:65]
	v_mfma_f32_16x16x32_bf16 v[58:61], v[142:145], v[170:173], v[58:61]
	v_mfma_f32_16x16x32_bf16 v[54:57], v[134:137], v[174:177], v[54:57]
	v_mfma_f32_16x16x32_bf16 v[50:53], v[142:145], v[174:177], v[50:53]
	v_mfma_f32_16x16x32_bf16 v[46:49], v[134:137], v[186:189], v[46:49]
	v_mfma_f32_16x16x32_bf16 v[42:45], v[142:145], v[186:189], v[42:45]
	v_mfma_f32_16x16x32_bf16 v[38:41], v[134:137], v[190:193], v[38:41]
	v_mfma_f32_16x16x32_bf16 v[34:37], v[142:145], v[190:193], v[34:37]
	v_mfma_f32_16x16x32_bf16 v[30:33], v[146:149], v[162:165], v[30:33]
	v_mfma_f32_16x16x32_bf16 v[26:29], v[154:157], v[162:165], v[26:29]
	v_mfma_f32_16x16x32_bf16 v[22:25], v[146:149], v[166:169], v[22:25]
	v_mfma_f32_16x16x32_bf16 v[18:21], v[154:157], v[166:169], v[18:21]
	v_mfma_f32_16x16x32_bf16 v[14:17], v[146:149], v[178:181], v[14:17]
	v_mfma_f32_16x16x32_bf16 v[10:13], v[154:157], v[178:181], v[10:13]
	v_mfma_f32_16x16x32_bf16 v[6:9], v[146:149], v[182:185], v[6:9]
	v_mfma_f32_16x16x32_bf16 v[2:5], v[154:157], v[182:185], v[2:5]
	v_mfma_f32_16x16x32_bf16 v[30:33], v[150:153], v[170:173], v[30:33]
	v_mfma_f32_16x16x32_bf16 v[26:29], v[158:161], v[170:173], v[26:29]
	v_mfma_f32_16x16x32_bf16 v[22:25], v[150:153], v[174:177], v[22:25]
	v_mfma_f32_16x16x32_bf16 v[18:21], v[158:161], v[174:177], v[18:21]
	v_mfma_f32_16x16x32_bf16 v[14:17], v[150:153], v[186:189], v[14:17]
	v_mfma_f32_16x16x32_bf16 v[10:13], v[158:161], v[186:189], v[10:13]
	v_mfma_f32_16x16x32_bf16 v[6:9], v[150:153], v[190:193], v[6:9]
	v_mfma_f32_16x16x32_bf16 v[2:5], v[158:161], v[190:193], v[2:5]
	s_barrier
	s_setprio 0
	ds_read_b128 v[130:133], v223
	ds_read_b128 v[134:137], v224
	ds_read_b128 v[138:141], v225
	ds_read_b128 v[142:145], v227
	ds_read_b128 v[146:149], v228
	ds_read_b128 v[150:153], v229
	ds_read_b128 v[154:157], v230
	ds_read_b128 v[158:161], v231
	s_add_i32 s84, s84, s80
	s_mov_b32 m0, s30
	ds_read_b128 v[162:165], v219 offset:32768
	ds_read_b128 v[166:169], v219 offset:34816
	ds_read_b128 v[170:173], v220 offset:32768
	ds_read_b128 v[174:177], v220 offset:34816
	ds_read_b128 v[178:181], v219 offset:36864
	ds_read_b128 v[182:185], v219 offset:38912
	ds_read_b128 v[186:189], v220 offset:36864
	ds_read_b128 v[190:193], v220 offset:38912
	buffer_load_dwordx4 v235, s[4:7], s84 offen lds
	s_mov_b32 m0, s31
	s_nop 0
	buffer_load_dwordx4 v236, s[4:7], s84 offen lds
	s_waitcnt vmcnt(8)
	s_waitcnt lgkmcnt(0)
	s_setprio 1
	v_mfma_f32_16x16x32_bf16 v[126:129], v[130:133], v[162:165], v[126:129]
	v_mfma_f32_16x16x32_bf16 v[122:125], v[138:141], v[162:165], v[122:125]
	v_mfma_f32_16x16x32_bf16 v[118:121], v[130:133], v[166:169], v[118:121]
	v_mfma_f32_16x16x32_bf16 v[114:117], v[138:141], v[166:169], v[114:117]
	s_barrier
	v_mfma_f32_16x16x32_bf16 v[110:113], v[130:133], v[178:181], v[110:113]
	v_mfma_f32_16x16x32_bf16 v[106:109], v[138:141], v[178:181], v[106:109]
	v_mfma_f32_16x16x32_bf16 v[102:105], v[130:133], v[182:185], v[102:105]
	v_mfma_f32_16x16x32_bf16 v[98:101], v[138:141], v[182:185], v[98:101]
	v_mfma_f32_16x16x32_bf16 v[126:129], v[134:137], v[170:173], v[126:129]
	v_mfma_f32_16x16x32_bf16 v[122:125], v[142:145], v[170:173], v[122:125]
	v_mfma_f32_16x16x32_bf16 v[118:121], v[134:137], v[174:177], v[118:121]
	v_mfma_f32_16x16x32_bf16 v[114:117], v[142:145], v[174:177], v[114:117]
	v_mfma_f32_16x16x32_bf16 v[110:113], v[134:137], v[186:189], v[110:113]
	v_mfma_f32_16x16x32_bf16 v[106:109], v[142:145], v[186:189], v[106:109]
	v_mfma_f32_16x16x32_bf16 v[102:105], v[134:137], v[190:193], v[102:105]
	v_mfma_f32_16x16x32_bf16 v[98:101], v[142:145], v[190:193], v[98:101]
	v_mfma_f32_16x16x32_bf16 v[94:97], v[146:149], v[162:165], v[94:97]
	v_mfma_f32_16x16x32_bf16 v[90:93], v[154:157], v[162:165], v[90:93]
	v_mfma_f32_16x16x32_bf16 v[86:89], v[146:149], v[166:169], v[86:89]
	v_mfma_f32_16x16x32_bf16 v[82:85], v[154:157], v[166:169], v[82:85]
	v_mfma_f32_16x16x32_bf16 v[78:81], v[146:149], v[178:181], v[78:81]
	v_mfma_f32_16x16x32_bf16 v[74:77], v[154:157], v[178:181], v[74:77]
	v_mfma_f32_16x16x32_bf16 v[70:73], v[146:149], v[182:185], v[70:73]
	v_mfma_f32_16x16x32_bf16 v[66:69], v[154:157], v[182:185], v[66:69]
	v_mfma_f32_16x16x32_bf16 v[94:97], v[150:153], v[170:173], v[94:97]
	v_mfma_f32_16x16x32_bf16 v[90:93], v[158:161], v[170:173], v[90:93]
	v_mfma_f32_16x16x32_bf16 v[86:89], v[150:153], v[174:177], v[86:89]
	v_mfma_f32_16x16x32_bf16 v[82:85], v[158:161], v[174:177], v[82:85]
	v_mfma_f32_16x16x32_bf16 v[78:81], v[150:153], v[186:189], v[78:81]
	v_mfma_f32_16x16x32_bf16 v[74:77], v[158:161], v[186:189], v[74:77]
	v_mfma_f32_16x16x32_bf16 v[70:73], v[150:153], v[190:193], v[70:73]
	v_mfma_f32_16x16x32_bf16 v[66:69], v[158:161], v[190:193], v[66:69]
	s_barrier
	s_setprio 0
	s_mov_b32 m0, s36
	s_addk_i32 s81, 0x80
	ds_read_b128 v[162:165], v219 offset:49152
	ds_read_b128 v[166:169], v219 offset:51200
	ds_read_b128 v[170:173], v220 offset:49152
	ds_read_b128 v[174:177], v220 offset:51200
	ds_read_b128 v[178:181], v219 offset:53248
	ds_read_b128 v[182:185], v219 offset:55296
	ds_read_b128 v[186:189], v220 offset:53248
	ds_read_b128 v[190:193], v220 offset:55296
	buffer_load_dwordx4 v233, s[4:7], s81 offen lds
	s_mov_b32 m0, s37
	s_nop 0
	buffer_load_dwordx4 v234, s[4:7], s81 offen lds
	s_add_i32 s81, s81, s80
	s_mov_b32 m0, s40
	s_nop 0
	buffer_load_dwordx4 v233, s[4:7], s81 offen lds
	s_mov_b32 m0, s41
	s_nop 0
	buffer_load_dwordx4 v234, s[4:7], s81 offen lds
	s_mov_b32 m0, s38
	s_nop 0
	buffer_load_dwordx4 v235, s[4:7], s79 offen lds
	s_mov_b32 m0, s39
	s_nop 0
	buffer_load_dwordx4 v236, s[4:7], s79 offen lds
	s_waitcnt vmcnt(8)
	s_waitcnt lgkmcnt(0)
	s_setprio 1
	v_mfma_f32_16x16x32_bf16 v[62:65], v[130:133], v[162:165], v[62:65]
	v_mfma_f32_16x16x32_bf16 v[58:61], v[138:141], v[162:165], v[58:61]
	s_barrier
	v_mfma_f32_16x16x32_bf16 v[54:57], v[130:133], v[166:169], v[54:57]
	v_mfma_f32_16x16x32_bf16 v[50:53], v[138:141], v[166:169], v[50:53]
	v_mfma_f32_16x16x32_bf16 v[46:49], v[130:133], v[178:181], v[46:49]
	v_mfma_f32_16x16x32_bf16 v[42:45], v[138:141], v[178:181], v[42:45]
	v_mfma_f32_16x16x32_bf16 v[38:41], v[130:133], v[182:185], v[38:41]
	v_mfma_f32_16x16x32_bf16 v[34:37], v[138:141], v[182:185], v[34:37]
	v_mfma_f32_16x16x32_bf16 v[62:65], v[134:137], v[170:173], v[62:65]
	v_mfma_f32_16x16x32_bf16 v[58:61], v[142:145], v[170:173], v[58:61]
	v_mfma_f32_16x16x32_bf16 v[54:57], v[134:137], v[174:177], v[54:57]
	v_mfma_f32_16x16x32_bf16 v[50:53], v[142:145], v[174:177], v[50:53]
	v_mfma_f32_16x16x32_bf16 v[46:49], v[134:137], v[186:189], v[46:49]
	v_mfma_f32_16x16x32_bf16 v[42:45], v[142:145], v[186:189], v[42:45]
	v_mfma_f32_16x16x32_bf16 v[38:41], v[134:137], v[190:193], v[38:41]
	v_mfma_f32_16x16x32_bf16 v[34:37], v[142:145], v[190:193], v[34:37]
	v_mfma_f32_16x16x32_bf16 v[30:33], v[146:149], v[162:165], v[30:33]
	v_mfma_f32_16x16x32_bf16 v[26:29], v[154:157], v[162:165], v[26:29]
	v_mfma_f32_16x16x32_bf16 v[22:25], v[146:149], v[166:169], v[22:25]
	v_mfma_f32_16x16x32_bf16 v[18:21], v[154:157], v[166:169], v[18:21]
	v_mfma_f32_16x16x32_bf16 v[14:17], v[146:149], v[178:181], v[14:17]
	v_mfma_f32_16x16x32_bf16 v[10:13], v[154:157], v[178:181], v[10:13]
	v_mfma_f32_16x16x32_bf16 v[6:9], v[146:149], v[182:185], v[6:9]
	v_mfma_f32_16x16x32_bf16 v[2:5], v[154:157], v[182:185], v[2:5]
	v_mfma_f32_16x16x32_bf16 v[30:33], v[150:153], v[170:173], v[30:33]
	v_mfma_f32_16x16x32_bf16 v[26:29], v[158:161], v[170:173], v[26:29]
	v_mfma_f32_16x16x32_bf16 v[22:25], v[150:153], v[174:177], v[22:25]
	v_mfma_f32_16x16x32_bf16 v[18:21], v[158:161], v[174:177], v[18:21]
	v_mfma_f32_16x16x32_bf16 v[14:17], v[150:153], v[186:189], v[14:17]
	v_mfma_f32_16x16x32_bf16 v[10:13], v[158:161], v[186:189], v[10:13]
	v_mfma_f32_16x16x32_bf16 v[6:9], v[150:153], v[190:193], v[6:9]
	v_mfma_f32_16x16x32_bf16 v[2:5], v[158:161], v[190:193], v[2:5]
	s_barrier
	s_setprio 0
	s_add_i32 s4, s78, 2
	s_addk_i32 s62, 0x100
	s_addk_i32 s61, 0x100
	s_cmp_ge_u32 s78, s63
	s_mov_b32 s78, s4
	s_cbranch_scc0 .LBB0_546
	s_and_b64 vcc, exec, s[12:13]
	s_cbranch_vccz .LBB0_549
	s_barrier

.LBB0_841:
	ds_read_b128 v[130:133], v240
	ds_read_b128 v[134:137], v241
	ds_read_b128 v[138:141], v242
	ds_read_b128 v[142:145], v243
	ds_read_b128 v[146:149], v244
	ds_read_b128 v[150:153], v245
	ds_read_b128 v[154:157], v246
	ds_read_b128 v[158:161], v247
	s_add_i32 s8, s42, s5
	s_add_i32 s19, s34, s5
	s_add_i32 s18, s8, 0x800
	s_addk_i32 s19, 0x800
	s_cmp_eq_u32 s5, 0
	s_cselect_b32 s20, s0, s18
	s_cselect_b32 s19, s1, s19
	s_add_i32 s18, s20, 0x80
	s_add_i32 s21, s8, 0x40780
	s_mov_b32 s8, s70
	s_mov_b32 m0, s52
	ds_read_b128 v[162:165], v248
	ds_read_b128 v[166:169], v248 offset:2048
	ds_read_b128 v[170:173], v249
	ds_read_b128 v[174:177], v249 offset:2048
	ds_read_b128 v[178:181], v248 offset:4096
	ds_read_b128 v[182:185], v248 offset:6144
	ds_read_b128 v[186:189], v249 offset:4096
	ds_read_b128 v[190:193], v249 offset:6144
	buffer_load_dwordx4 v1, s[8:11], s21 offen lds
	s_mov_b32 m0, s53
	s_nop 0
	buffer_load_dwordx4 v234, s[8:11], s21 offen lds
	s_waitcnt vmcnt(8)
	s_waitcnt lgkmcnt(0)
	s_setprio 1
	v_mfma_f32_16x16x32_bf16 v[74:77], v[130:133], v[162:165], v[74:77]
	v_mfma_f32_16x16x32_bf16 v[70:73], v[138:141], v[162:165], v[70:73]
	v_mfma_f32_16x16x32_bf16 v[66:69], v[130:133], v[166:169], v[66:69]
	v_mfma_f32_16x16x32_bf16 v[82:85], v[138:141], v[166:169], v[82:85]
	s_barrier
	v_mfma_f32_16x16x32_bf16 v[78:81], v[130:133], v[178:181], v[78:81]
	v_mfma_f32_16x16x32_bf16 v[90:93], v[138:141], v[178:181], v[90:93]
	v_mfma_f32_16x16x32_bf16 v[86:89], v[130:133], v[182:185], v[86:89]
	v_mfma_f32_16x16x32_bf16 v[102:105], v[138:141], v[182:185], v[102:105]
	v_mfma_f32_16x16x32_bf16 v[74:77], v[134:137], v[170:173], v[74:77]
	v_mfma_f32_16x16x32_bf16 v[70:73], v[142:145], v[170:173], v[70:73]
	v_mfma_f32_16x16x32_bf16 v[66:69], v[134:137], v[174:177], v[66:69]
	v_mfma_f32_16x16x32_bf16 v[82:85], v[142:145], v[174:177], v[82:85]
	v_mfma_f32_16x16x32_bf16 v[78:81], v[134:137], v[186:189], v[78:81]
	v_mfma_f32_16x16x32_bf16 v[90:93], v[142:145], v[186:189], v[90:93]
	v_mfma_f32_16x16x32_bf16 v[86:89], v[134:137], v[190:193], v[86:89]
	v_mfma_f32_16x16x32_bf16 v[102:105], v[142:145], v[190:193], v[102:105]
	v_mfma_f32_16x16x32_bf16 v[98:101], v[146:149], v[162:165], v[98:101]
	v_mfma_f32_16x16x32_bf16 v[94:97], v[154:157], v[162:165], v[94:97]
	v_mfma_f32_16x16x32_bf16 v[106:109], v[146:149], v[166:169], v[106:109]
	v_mfma_f32_16x16x32_bf16 v[110:113], v[154:157], v[166:169], v[110:113]
	v_mfma_f32_16x16x32_bf16 v[114:117], v[146:149], v[178:181], v[114:117]
	v_mfma_f32_16x16x32_bf16 v[118:121], v[154:157], v[178:181], v[118:121]
	v_mfma_f32_16x16x32_bf16 v[122:125], v[146:149], v[182:185], v[122:125]
	v_mfma_f32_16x16x32_bf16 v[126:129], v[154:157], v[182:185], v[126:129]
	v_mfma_f32_16x16x32_bf16 v[98:101], v[150:153], v[170:173], v[98:101]
	v_mfma_f32_16x16x32_bf16 v[94:97], v[158:161], v[170:173], v[94:97]
	v_mfma_f32_16x16x32_bf16 v[106:109], v[150:153], v[174:177], v[106:109]
	v_mfma_f32_16x16x32_bf16 v[110:113], v[158:161], v[174:177], v[110:113]
	v_mfma_f32_16x16x32_bf16 v[114:117], v[150:153], v[186:189], v[114:117]
	v_mfma_f32_16x16x32_bf16 v[118:121], v[158:161], v[186:189], v[118:121]
	v_mfma_f32_16x16x32_bf16 v[122:125], v[150:153], v[190:193], v[122:125]
	v_mfma_f32_16x16x32_bf16 v[126:129], v[158:161], v[190:193], v[126:129]
	s_barrier
	s_setprio 0
	s_mov_b32 m0, s29
	ds_read_b128 v[162:165], v248 offset:16384
	ds_read_b128 v[166:169], v248 offset:18432
	ds_read_b128 v[170:173], v249 offset:16384
	ds_read_b128 v[174:177], v249 offset:18432
	ds_read_b128 v[178:181], v248 offset:20480
	ds_read_b128 v[182:185], v248 offset:22528
	ds_read_b128 v[186:189], v249 offset:20480
	ds_read_b128 v[190:193], v249 offset:22528
	buffer_load_dwordx4 v233, s[8:11], s19 offen lds
	s_mov_b32 m0, s30
	s_add_i32 s21, s19, 0x40000
	buffer_load_dwordx4 v235, s[8:11], s19 offen lds
	s_mov_b32 m0, s31
	s_nop 0
	buffer_load_dwordx4 v233, s[8:11], s21 offen lds
	s_mov_b32 m0, s35
	s_nop 0
	buffer_load_dwordx4 v235, s[8:11], s21 offen lds
	s_mov_b32 m0, s28
	s_nop 0
	buffer_load_dwordx4 v1, s[8:11], s20 offen lds
	s_mov_b32 m0, s38
	s_nop 0
	buffer_load_dwordx4 v234, s[8:11], s20 offen lds
	s_waitcnt vmcnt(8)
	s_waitcnt lgkmcnt(0)
	s_setprio 1
	v_mfma_f32_16x16x32_bf16 v[10:13], v[130:133], v[162:165], v[10:13]
	v_mfma_f32_16x16x32_bf16 v[6:9], v[138:141], v[162:165], v[6:9]
	s_barrier
	v_mfma_f32_16x16x32_bf16 v[2:5], v[130:133], v[166:169], v[2:5]
	v_mfma_f32_16x16x32_bf16 v[18:21], v[138:141], v[166:169], v[18:21]
	v_mfma_f32_16x16x32_bf16 v[14:17], v[130:133], v[178:181], v[14:17]
	v_mfma_f32_16x16x32_bf16 v[26:29], v[138:141], v[178:181], v[26:29]
	v_mfma_f32_16x16x32_bf16 v[22:25], v[130:133], v[182:185], v[22:25]
	v_mfma_f32_16x16x32_bf16 v[38:41], v[138:141], v[182:185], v[38:41]
	v_mfma_f32_16x16x32_bf16 v[10:13], v[134:137], v[170:173], v[10:13]
	v_mfma_f32_16x16x32_bf16 v[6:9], v[142:145], v[170:173], v[6:9]
	v_mfma_f32_16x16x32_bf16 v[2:5], v[134:137], v[174:177], v[2:5]
	v_mfma_f32_16x16x32_bf16 v[18:21], v[142:145], v[174:177], v[18:21]
	v_mfma_f32_16x16x32_bf16 v[14:17], v[134:137], v[186:189], v[14:17]
	v_mfma_f32_16x16x32_bf16 v[26:29], v[142:145], v[186:189], v[26:29]
	v_mfma_f32_16x16x32_bf16 v[22:25], v[134:137], v[190:193], v[22:25]
	v_mfma_f32_16x16x32_bf16 v[38:41], v[142:145], v[190:193], v[38:41]
	v_mfma_f32_16x16x32_bf16 v[34:37], v[146:149], v[162:165], v[34:37]
	v_mfma_f32_16x16x32_bf16 v[30:33], v[154:157], v[162:165], v[30:33]
	v_mfma_f32_16x16x32_bf16 v[42:45], v[146:149], v[166:169], v[42:45]
	v_mfma_f32_16x16x32_bf16 v[46:49], v[154:157], v[166:169], v[46:49]
	v_mfma_f32_16x16x32_bf16 v[50:53], v[146:149], v[178:181], v[50:53]
	v_mfma_f32_16x16x32_bf16 v[54:57], v[154:157], v[178:181], v[54:57]
	v_mfma_f32_16x16x32_bf16 v[58:61], v[146:149], v[182:185], v[58:61]
	v_mfma_f32_16x16x32_bf16 v[62:65], v[154:157], v[182:185], v[62:65]
	v_mfma_f32_16x16x32_bf16 v[34:37], v[150:153], v[170:173], v[34:37]
	v_mfma_f32_16x16x32_bf16 v[30:33], v[158:161], v[170:173], v[30:33]
	v_mfma_f32_16x16x32_bf16 v[42:45], v[150:153], v[174:177], v[42:45]
	v_mfma_f32_16x16x32_bf16 v[46:49], v[158:161], v[174:177], v[46:49]
	v_mfma_f32_16x16x32_bf16 v[50:53], v[150:153], v[186:189], v[50:53]
	v_mfma_f32_16x16x32_bf16 v[54:57], v[158:161], v[186:189], v[54:57]
	v_mfma_f32_16x16x32_bf16 v[58:61], v[150:153], v[190:193], v[58:61]
	v_mfma_f32_16x16x32_bf16 v[62:65], v[158:161], v[190:193], v[62:65]
	s_barrier
	s_setprio 0
	ds_read_b128 v[130:133], v194
	ds_read_b128 v[134:137], v195
	ds_read_b128 v[138:141], v196
	ds_read_b128 v[142:145], v197
	ds_read_b128 v[146:149], v198
	ds_read_b128 v[150:153], v199
	ds_read_b128 v[154:157], v200
	ds_read_b128 v[158:161], v201
	s_add_i32 s20, s20, 0x40000
	s_mov_b32 m0, s39
	ds_read_b128 v[162:165], v248 offset:32768
	ds_read_b128 v[166:169], v248 offset:34816
	ds_read_b128 v[170:173], v249 offset:32768
	ds_read_b128 v[174:177], v249 offset:34816
	ds_read_b128 v[178:181], v248 offset:36864
	ds_read_b128 v[182:185], v248 offset:38912
	ds_read_b128 v[186:189], v249 offset:36864
	ds_read_b128 v[190:193], v249 offset:38912
	buffer_load_dwordx4 v1, s[8:11], s20 offen lds
	s_mov_b32 m0, s41
	s_nop 0
	buffer_load_dwordx4 v234, s[8:11], s20 offen lds
	s_waitcnt vmcnt(8)
	s_waitcnt lgkmcnt(0)
	s_setprio 1
	v_mfma_f32_16x16x32_bf16 v[74:77], v[130:133], v[162:165], v[74:77]
	v_mfma_f32_16x16x32_bf16 v[70:73], v[138:141], v[162:165], v[70:73]
	v_mfma_f32_16x16x32_bf16 v[66:69], v[130:133], v[166:169], v[66:69]
	v_mfma_f32_16x16x32_bf16 v[82:85], v[138:141], v[166:169], v[82:85]
	s_barrier
	v_mfma_f32_16x16x32_bf16 v[78:81], v[130:133], v[178:181], v[78:81]
	v_mfma_f32_16x16x32_bf16 v[90:93], v[138:141], v[178:181], v[90:93]
	v_mfma_f32_16x16x32_bf16 v[86:89], v[130:133], v[182:185], v[86:89]
	v_mfma_f32_16x16x32_bf16 v[102:105], v[138:141], v[182:185], v[102:105]
	v_mfma_f32_16x16x32_bf16 v[74:77], v[134:137], v[170:173], v[74:77]
	v_mfma_f32_16x16x32_bf16 v[70:73], v[142:145], v[170:173], v[70:73]
	v_mfma_f32_16x16x32_bf16 v[66:69], v[134:137], v[174:177], v[66:69]
	v_mfma_f32_16x16x32_bf16 v[82:85], v[142:145], v[174:177], v[82:85]
	v_mfma_f32_16x16x32_bf16 v[78:81], v[134:137], v[186:189], v[78:81]
	v_mfma_f32_16x16x32_bf16 v[90:93], v[142:145], v[186:189], v[90:93]
	v_mfma_f32_16x16x32_bf16 v[86:89], v[134:137], v[190:193], v[86:89]
	v_mfma_f32_16x16x32_bf16 v[102:105], v[142:145], v[190:193], v[102:105]
	v_mfma_f32_16x16x32_bf16 v[98:101], v[146:149], v[162:165], v[98:101]
	v_mfma_f32_16x16x32_bf16 v[94:97], v[154:157], v[162:165], v[94:97]
	v_mfma_f32_16x16x32_bf16 v[106:109], v[146:149], v[166:169], v[106:109]
	v_mfma_f32_16x16x32_bf16 v[110:113], v[154:157], v[166:169], v[110:113]
	v_mfma_f32_16x16x32_bf16 v[114:117], v[146:149], v[178:181], v[114:117]
	v_mfma_f32_16x16x32_bf16 v[118:121], v[154:157], v[178:181], v[118:121]
	v_mfma_f32_16x16x32_bf16 v[122:125], v[146:149], v[182:185], v[122:125]
	v_mfma_f32_16x16x32_bf16 v[126:129], v[154:157], v[182:185], v[126:129]
	v_mfma_f32_16x16x32_bf16 v[98:101], v[150:153], v[170:173], v[98:101]
	v_mfma_f32_16x16x32_bf16 v[94:97], v[158:161], v[170:173], v[94:97]
	v_mfma_f32_16x16x32_bf16 v[106:109], v[150:153], v[174:177], v[106:109]
	v_mfma_f32_16x16x32_bf16 v[110:113], v[158:161], v[174:177], v[110:113]
	v_mfma_f32_16x16x32_bf16 v[114:117], v[150:153], v[186:189], v[114:117]
	v_mfma_f32_16x16x32_bf16 v[118:121], v[158:161], v[186:189], v[118:121]
	v_mfma_f32_16x16x32_bf16 v[122:125], v[150:153], v[190:193], v[122:125]
	v_mfma_f32_16x16x32_bf16 v[126:129], v[158:161], v[190:193], v[126:129]
	s_barrier
	s_setprio 0
	s_mov_b32 m0, s44
	s_add_i32 s20, s19, 0x80
	ds_read_b128 v[162:165], v248 offset:49152
	ds_read_b128 v[166:169], v248 offset:51200
	ds_read_b128 v[170:173], v249 offset:49152
	ds_read_b128 v[174:177], v249 offset:51200
	ds_read_b128 v[178:181], v248 offset:53248
	ds_read_b128 v[182:185], v248 offset:55296
	ds_read_b128 v[186:189], v249 offset:53248
	ds_read_b128 v[190:193], v249 offset:55296
	buffer_load_dwordx4 v233, s[8:11], s20 offen lds
	s_mov_b32 m0, s45
	s_add_i32 s19, s19, 0x40080
	buffer_load_dwordx4 v235, s[8:11], s20 offen lds
	s_mov_b32 m0, s48
	s_nop 0
	buffer_load_dwordx4 v233, s[8:11], s19 offen lds
	s_mov_b32 m0, s49
	s_nop 0
	buffer_load_dwordx4 v235, s[8:11], s19 offen lds
	s_mov_b32 m0, s46
	s_nop 0
	buffer_load_dwordx4 v1, s[8:11], s18 offen lds
	s_mov_b32 m0, s47
	s_nop 0
	buffer_load_dwordx4 v234, s[8:11], s18 offen lds
	s_waitcnt vmcnt(8)
	s_waitcnt lgkmcnt(0)
	s_setprio 1
	v_mfma_f32_16x16x32_bf16 v[10:13], v[130:133], v[162:165], v[10:13]
	v_mfma_f32_16x16x32_bf16 v[6:9], v[138:141], v[162:165], v[6:9]
	s_barrier
	v_mfma_f32_16x16x32_bf16 v[2:5], v[130:133], v[166:169], v[2:5]
	v_mfma_f32_16x16x32_bf16 v[18:21], v[138:141], v[166:169], v[18:21]
	v_mfma_f32_16x16x32_bf16 v[14:17], v[130:133], v[178:181], v[14:17]
	v_mfma_f32_16x16x32_bf16 v[26:29], v[138:141], v[178:181], v[26:29]
	v_mfma_f32_16x16x32_bf16 v[22:25], v[130:133], v[182:185], v[22:25]
	v_mfma_f32_16x16x32_bf16 v[38:41], v[138:141], v[182:185], v[38:41]
	v_mfma_f32_16x16x32_bf16 v[10:13], v[134:137], v[170:173], v[10:13]
	v_mfma_f32_16x16x32_bf16 v[6:9], v[142:145], v[170:173], v[6:9]
	v_mfma_f32_16x16x32_bf16 v[2:5], v[134:137], v[174:177], v[2:5]
	v_mfma_f32_16x16x32_bf16 v[18:21], v[142:145], v[174:177], v[18:21]
	v_mfma_f32_16x16x32_bf16 v[14:17], v[134:137], v[186:189], v[14:17]
	v_mfma_f32_16x16x32_bf16 v[26:29], v[142:145], v[186:189], v[26:29]
	v_mfma_f32_16x16x32_bf16 v[22:25], v[134:137], v[190:193], v[22:25]
	v_mfma_f32_16x16x32_bf16 v[38:41], v[142:145], v[190:193], v[38:41]
	v_mfma_f32_16x16x32_bf16 v[34:37], v[146:149], v[162:165], v[34:37]
	v_mfma_f32_16x16x32_bf16 v[30:33], v[154:157], v[162:165], v[30:33]
	v_mfma_f32_16x16x32_bf16 v[42:45], v[146:149], v[166:169], v[42:45]
	v_mfma_f32_16x16x32_bf16 v[46:49], v[154:157], v[166:169], v[46:49]
	v_mfma_f32_16x16x32_bf16 v[50:53], v[146:149], v[178:181], v[50:53]
	v_mfma_f32_16x16x32_bf16 v[54:57], v[154:157], v[178:181], v[54:57]
	v_mfma_f32_16x16x32_bf16 v[58:61], v[146:149], v[182:185], v[58:61]
	v_mfma_f32_16x16x32_bf16 v[62:65], v[154:157], v[182:185], v[62:65]
	v_mfma_f32_16x16x32_bf16 v[34:37], v[150:153], v[170:173], v[34:37]
	v_mfma_f32_16x16x32_bf16 v[30:33], v[158:161], v[170:173], v[30:33]
	v_mfma_f32_16x16x32_bf16 v[42:45], v[150:153], v[174:177], v[42:45]
	v_mfma_f32_16x16x32_bf16 v[46:49], v[158:161], v[174:177], v[46:49]
	v_mfma_f32_16x16x32_bf16 v[50:53], v[150:153], v[186:189], v[50:53]
	v_mfma_f32_16x16x32_bf16 v[54:57], v[158:161], v[186:189], v[54:57]
	v_mfma_f32_16x16x32_bf16 v[58:61], v[150:153], v[190:193], v[58:61]
	v_mfma_f32_16x16x32_bf16 v[62:65], v[158:161], v[190:193], v[62:65]
	s_barrier
	s_setprio 0
	s_add_i32 s4, s4, 2
	s_addk_i32 s5, 0x100
	s_cmp_gt_u32 s4, 13
	s_cbranch_scc0 .LBB0_841
	s_and_b64 vcc, exec, s[16:17]
	s_cbranch_vccz .LBB0_844
	s_barrier

.LBB0_1122:
	ds_read_b128 v[130:133], v240
	ds_read_b128 v[134:137], v241
	ds_read_b128 v[138:141], v242
	ds_read_b128 v[142:145], v243
	ds_read_b128 v[146:149], v244
	ds_read_b128 v[150:153], v245
	ds_read_b128 v[154:157], v246
	ds_read_b128 v[158:161], v247
	s_add_i32 s8, s31, s53
	s_add_i32 s55, s26, s53
	s_add_i32 s54, s8, 0x800
	s_addk_i32 s55, 0x800
	s_cmp_eq_u32 s53, 0
	s_cselect_b32 s56, s4, s54
	s_cselect_b32 s55, s5, s55
	s_add_i32 s54, s56, 0x80
	s_add_i32 s57, s8, 0x40780
	s_mov_b32 s8, s70
	s_mov_b32 m0, s44
	ds_read_b128 v[162:165], v248
	ds_read_b128 v[166:169], v248 offset:2048
	ds_read_b128 v[170:173], v249
	ds_read_b128 v[174:177], v249 offset:2048
	ds_read_b128 v[178:181], v248 offset:4096
	ds_read_b128 v[182:185], v248 offset:6144
	ds_read_b128 v[186:189], v249 offset:4096
	ds_read_b128 v[190:193], v249 offset:6144
	buffer_load_dwordx4 v1, s[8:11], s57 offen lds
	s_mov_b32 m0, s45
	s_nop 0
	buffer_load_dwordx4 v234, s[8:11], s57 offen lds
	s_waitcnt vmcnt(8)
	s_waitcnt lgkmcnt(0)
	s_setprio 1
	v_mfma_f32_16x16x32_bf16 v[126:129], v[130:133], v[162:165], v[126:129]
	v_mfma_f32_16x16x32_bf16 v[122:125], v[138:141], v[162:165], v[122:125]
	v_mfma_f32_16x16x32_bf16 v[118:121], v[130:133], v[166:169], v[118:121]
	v_mfma_f32_16x16x32_bf16 v[114:117], v[138:141], v[166:169], v[114:117]
	s_barrier
	v_mfma_f32_16x16x32_bf16 v[110:113], v[130:133], v[178:181], v[110:113]
	v_mfma_f32_16x16x32_bf16 v[106:109], v[138:141], v[178:181], v[106:109]
	v_mfma_f32_16x16x32_bf16 v[102:105], v[130:133], v[182:185], v[102:105]
	v_mfma_f32_16x16x32_bf16 v[98:101], v[138:141], v[182:185], v[98:101]
	v_mfma_f32_16x16x32_bf16 v[126:129], v[134:137], v[170:173], v[126:129]
	v_mfma_f32_16x16x32_bf16 v[122:125], v[142:145], v[170:173], v[122:125]
	v_mfma_f32_16x16x32_bf16 v[118:121], v[134:137], v[174:177], v[118:121]
	v_mfma_f32_16x16x32_bf16 v[114:117], v[142:145], v[174:177], v[114:117]
	v_mfma_f32_16x16x32_bf16 v[110:113], v[134:137], v[186:189], v[110:113]
	v_mfma_f32_16x16x32_bf16 v[106:109], v[142:145], v[186:189], v[106:109]
	v_mfma_f32_16x16x32_bf16 v[102:105], v[134:137], v[190:193], v[102:105]
	v_mfma_f32_16x16x32_bf16 v[98:101], v[142:145], v[190:193], v[98:101]
	v_mfma_f32_16x16x32_bf16 v[94:97], v[146:149], v[162:165], v[94:97]
	v_mfma_f32_16x16x32_bf16 v[90:93], v[154:157], v[162:165], v[90:93]
	v_mfma_f32_16x16x32_bf16 v[86:89], v[146:149], v[166:169], v[86:89]
	v_mfma_f32_16x16x32_bf16 v[82:85], v[154:157], v[166:169], v[82:85]
	v_mfma_f32_16x16x32_bf16 v[78:81], v[146:149], v[178:181], v[78:81]
	v_mfma_f32_16x16x32_bf16 v[74:77], v[154:157], v[178:181], v[74:77]
	v_mfma_f32_16x16x32_bf16 v[70:73], v[146:149], v[182:185], v[70:73]
	v_mfma_f32_16x16x32_bf16 v[66:69], v[154:157], v[182:185], v[66:69]
	v_mfma_f32_16x16x32_bf16 v[94:97], v[150:153], v[170:173], v[94:97]
	v_mfma_f32_16x16x32_bf16 v[90:93], v[158:161], v[170:173], v[90:93]
	v_mfma_f32_16x16x32_bf16 v[86:89], v[150:153], v[174:177], v[86:89]
	v_mfma_f32_16x16x32_bf16 v[82:85], v[158:161], v[174:177], v[82:85]
	v_mfma_f32_16x16x32_bf16 v[78:81], v[150:153], v[186:189], v[78:81]
	v_mfma_f32_16x16x32_bf16 v[74:77], v[158:161], v[186:189], v[74:77]
	v_mfma_f32_16x16x32_bf16 v[70:73], v[150:153], v[190:193], v[70:73]
	v_mfma_f32_16x16x32_bf16 v[66:69], v[158:161], v[190:193], v[66:69]
	s_barrier
	s_setprio 0
	s_mov_b32 m0, s23
	ds_read_b128 v[162:165], v248 offset:16384
	ds_read_b128 v[166:169], v248 offset:18432
	ds_read_b128 v[170:173], v249 offset:16384
	ds_read_b128 v[174:177], v249 offset:18432
	ds_read_b128 v[178:181], v248 offset:20480
	ds_read_b128 v[182:185], v248 offset:22528
	ds_read_b128 v[186:189], v249 offset:20480
	ds_read_b128 v[190:193], v249 offset:22528
	buffer_load_dwordx4 v233, s[8:11], s55 offen lds
	s_mov_b32 m0, s24
	s_add_i32 s57, s55, 0x40000
	buffer_load_dwordx4 v235, s[8:11], s55 offen lds
	s_mov_b32 m0, s25
	s_nop 0
	buffer_load_dwordx4 v233, s[8:11], s57 offen lds
	s_mov_b32 m0, s27
	s_nop 0
	buffer_load_dwordx4 v235, s[8:11], s57 offen lds
	s_mov_b32 m0, s22
	s_nop 0
	buffer_load_dwordx4 v1, s[8:11], s56 offen lds
	s_mov_b32 m0, s28
	s_nop 0
	buffer_load_dwordx4 v234, s[8:11], s56 offen lds
	s_waitcnt vmcnt(8)
	s_waitcnt lgkmcnt(0)
	s_setprio 1
	v_mfma_f32_16x16x32_bf16 v[62:65], v[130:133], v[162:165], v[62:65]
	v_mfma_f32_16x16x32_bf16 v[58:61], v[138:141], v[162:165], v[58:61]
	s_barrier
	v_mfma_f32_16x16x32_bf16 v[54:57], v[130:133], v[166:169], v[54:57]
	v_mfma_f32_16x16x32_bf16 v[50:53], v[138:141], v[166:169], v[50:53]
	v_mfma_f32_16x16x32_bf16 v[46:49], v[130:133], v[178:181], v[46:49]
	v_mfma_f32_16x16x32_bf16 v[42:45], v[138:141], v[178:181], v[42:45]
	v_mfma_f32_16x16x32_bf16 v[38:41], v[130:133], v[182:185], v[38:41]
	v_mfma_f32_16x16x32_bf16 v[34:37], v[138:141], v[182:185], v[34:37]
	v_mfma_f32_16x16x32_bf16 v[62:65], v[134:137], v[170:173], v[62:65]
	v_mfma_f32_16x16x32_bf16 v[58:61], v[142:145], v[170:173], v[58:61]
	v_mfma_f32_16x16x32_bf16 v[54:57], v[134:137], v[174:177], v[54:57]
	v_mfma_f32_16x16x32_bf16 v[50:53], v[142:145], v[174:177], v[50:53]
	v_mfma_f32_16x16x32_bf16 v[46:49], v[134:137], v[186:189], v[46:49]
	v_mfma_f32_16x16x32_bf16 v[42:45], v[142:145], v[186:189], v[42:45]
	v_mfma_f32_16x16x32_bf16 v[38:41], v[134:137], v[190:193], v[38:41]
	v_mfma_f32_16x16x32_bf16 v[34:37], v[142:145], v[190:193], v[34:37]
	v_mfma_f32_16x16x32_bf16 v[30:33], v[146:149], v[162:165], v[30:33]
	v_mfma_f32_16x16x32_bf16 v[26:29], v[154:157], v[162:165], v[26:29]
	v_mfma_f32_16x16x32_bf16 v[22:25], v[146:149], v[166:169], v[22:25]
	v_mfma_f32_16x16x32_bf16 v[18:21], v[154:157], v[166:169], v[18:21]
	v_mfma_f32_16x16x32_bf16 v[14:17], v[146:149], v[178:181], v[14:17]
	v_mfma_f32_16x16x32_bf16 v[10:13], v[154:157], v[178:181], v[10:13]
	v_mfma_f32_16x16x32_bf16 v[6:9], v[146:149], v[182:185], v[6:9]
	v_mfma_f32_16x16x32_bf16 v[2:5], v[154:157], v[182:185], v[2:5]
	v_mfma_f32_16x16x32_bf16 v[30:33], v[150:153], v[170:173], v[30:33]
	v_mfma_f32_16x16x32_bf16 v[26:29], v[158:161], v[170:173], v[26:29]
	v_mfma_f32_16x16x32_bf16 v[22:25], v[150:153], v[174:177], v[22:25]
	v_mfma_f32_16x16x32_bf16 v[18:21], v[158:161], v[174:177], v[18:21]
	v_mfma_f32_16x16x32_bf16 v[14:17], v[150:153], v[186:189], v[14:17]
	v_mfma_f32_16x16x32_bf16 v[10:13], v[158:161], v[186:189], v[10:13]
	v_mfma_f32_16x16x32_bf16 v[6:9], v[150:153], v[190:193], v[6:9]
	v_mfma_f32_16x16x32_bf16 v[2:5], v[158:161], v[190:193], v[2:5]
	s_barrier
	s_setprio 0
	ds_read_b128 v[130:133], v194
	ds_read_b128 v[134:137], v195
	ds_read_b128 v[138:141], v196
	ds_read_b128 v[142:145], v197
	ds_read_b128 v[146:149], v198
	ds_read_b128 v[150:153], v199
	ds_read_b128 v[154:157], v200
	ds_read_b128 v[158:161], v201
	s_add_i32 s56, s56, 0x40000
	s_mov_b32 m0, s29
	ds_read_b128 v[162:165], v248 offset:32768
	ds_read_b128 v[166:169], v248 offset:34816
	ds_read_b128 v[170:173], v249 offset:32768
	ds_read_b128 v[174:177], v249 offset:34816
	ds_read_b128 v[178:181], v248 offset:36864
	ds_read_b128 v[182:185], v248 offset:38912
	ds_read_b128 v[186:189], v249 offset:36864
	ds_read_b128 v[190:193], v249 offset:38912
	buffer_load_dwordx4 v1, s[8:11], s56 offen lds
	s_mov_b32 m0, s30
	s_nop 0
	buffer_load_dwordx4 v234, s[8:11], s56 offen lds
	s_waitcnt vmcnt(8)
	s_waitcnt lgkmcnt(0)
	s_setprio 1
	v_mfma_f32_16x16x32_bf16 v[126:129], v[130:133], v[162:165], v[126:129]
	v_mfma_f32_16x16x32_bf16 v[122:125], v[138:141], v[162:165], v[122:125]
	v_mfma_f32_16x16x32_bf16 v[118:121], v[130:133], v[166:169], v[118:121]
	v_mfma_f32_16x16x32_bf16 v[114:117], v[138:141], v[166:169], v[114:117]
	s_barrier
	v_mfma_f32_16x16x32_bf16 v[110:113], v[130:133], v[178:181], v[110:113]
	v_mfma_f32_16x16x32_bf16 v[106:109], v[138:141], v[178:181], v[106:109]
	v_mfma_f32_16x16x32_bf16 v[102:105], v[130:133], v[182:185], v[102:105]
	v_mfma_f32_16x16x32_bf16 v[98:101], v[138:141], v[182:185], v[98:101]
	v_mfma_f32_16x16x32_bf16 v[126:129], v[134:137], v[170:173], v[126:129]
	v_mfma_f32_16x16x32_bf16 v[122:125], v[142:145], v[170:173], v[122:125]
	v_mfma_f32_16x16x32_bf16 v[118:121], v[134:137], v[174:177], v[118:121]
	v_mfma_f32_16x16x32_bf16 v[114:117], v[142:145], v[174:177], v[114:117]
	v_mfma_f32_16x16x32_bf16 v[110:113], v[134:137], v[186:189], v[110:113]
	v_mfma_f32_16x16x32_bf16 v[106:109], v[142:145], v[186:189], v[106:109]
	v_mfma_f32_16x16x32_bf16 v[102:105], v[134:137], v[190:193], v[102:105]
	v_mfma_f32_16x16x32_bf16 v[98:101], v[142:145], v[190:193], v[98:101]
	v_mfma_f32_16x16x32_bf16 v[94:97], v[146:149], v[162:165], v[94:97]
	v_mfma_f32_16x16x32_bf16 v[90:93], v[154:157], v[162:165], v[90:93]
	v_mfma_f32_16x16x32_bf16 v[86:89], v[146:149], v[166:169], v[86:89]
	v_mfma_f32_16x16x32_bf16 v[82:85], v[154:157], v[166:169], v[82:85]
	v_mfma_f32_16x16x32_bf16 v[78:81], v[146:149], v[178:181], v[78:81]
	v_mfma_f32_16x16x32_bf16 v[74:77], v[154:157], v[178:181], v[74:77]
	v_mfma_f32_16x16x32_bf16 v[70:73], v[146:149], v[182:185], v[70:73]
	v_mfma_f32_16x16x32_bf16 v[66:69], v[154:157], v[182:185], v[66:69]
	v_mfma_f32_16x16x32_bf16 v[94:97], v[150:153], v[170:173], v[94:97]
	v_mfma_f32_16x16x32_bf16 v[90:93], v[158:161], v[170:173], v[90:93]
	v_mfma_f32_16x16x32_bf16 v[86:89], v[150:153], v[174:177], v[86:89]
	v_mfma_f32_16x16x32_bf16 v[82:85], v[158:161], v[174:177], v[82:85]
	v_mfma_f32_16x16x32_bf16 v[78:81], v[150:153], v[186:189], v[78:81]
	v_mfma_f32_16x16x32_bf16 v[74:77], v[158:161], v[186:189], v[74:77]
	v_mfma_f32_16x16x32_bf16 v[70:73], v[150:153], v[190:193], v[70:73]
	v_mfma_f32_16x16x32_bf16 v[66:69], v[158:161], v[190:193], v[66:69]
	s_barrier
	s_setprio 0
	s_mov_b32 m0, s35
	s_add_i32 s56, s55, 0x80
	ds_read_b128 v[162:165], v248 offset:49152
	ds_read_b128 v[166:169], v248 offset:51200
	ds_read_b128 v[170:173], v249 offset:49152
	ds_read_b128 v[174:177], v249 offset:51200
	ds_read_b128 v[178:181], v248 offset:53248
	ds_read_b128 v[182:185], v248 offset:55296
	ds_read_b128 v[186:189], v249 offset:53248
	ds_read_b128 v[190:193], v249 offset:55296
	buffer_load_dwordx4 v233, s[8:11], s56 offen lds
	s_mov_b32 m0, s36
	s_add_i32 s55, s55, 0x40080
	buffer_load_dwordx4 v235, s[8:11], s56 offen lds
	s_mov_b32 m0, s39
	s_nop 0
	buffer_load_dwordx4 v233, s[8:11], s55 offen lds
	s_mov_b32 m0, s41
	s_nop 0
	buffer_load_dwordx4 v235, s[8:11], s55 offen lds
	s_mov_b32 m0, s37
	s_nop 0
	buffer_load_dwordx4 v1, s[8:11], s54 offen lds
	s_mov_b32 m0, s38
	s_nop 0
	buffer_load_dwordx4 v234, s[8:11], s54 offen lds
	s_waitcnt vmcnt(8)
	s_waitcnt lgkmcnt(0)
	s_setprio 1
	v_mfma_f32_16x16x32_bf16 v[62:65], v[130:133], v[162:165], v[62:65]
	v_mfma_f32_16x16x32_bf16 v[58:61], v[138:141], v[162:165], v[58:61]
	s_barrier
	v_mfma_f32_16x16x32_bf16 v[54:57], v[130:133], v[166:169], v[54:57]
	v_mfma_f32_16x16x32_bf16 v[50:53], v[138:141], v[166:169], v[50:53]
	v_mfma_f32_16x16x32_bf16 v[46:49], v[130:133], v[178:181], v[46:49]
	v_mfma_f32_16x16x32_bf16 v[42:45], v[138:141], v[178:181], v[42:45]
	v_mfma_f32_16x16x32_bf16 v[38:41], v[130:133], v[182:185], v[38:41]
	v_mfma_f32_16x16x32_bf16 v[34:37], v[138:141], v[182:185], v[34:37]
	v_mfma_f32_16x16x32_bf16 v[62:65], v[134:137], v[170:173], v[62:65]
	v_mfma_f32_16x16x32_bf16 v[58:61], v[142:145], v[170:173], v[58:61]
	v_mfma_f32_16x16x32_bf16 v[54:57], v[134:137], v[174:177], v[54:57]
	v_mfma_f32_16x16x32_bf16 v[50:53], v[142:145], v[174:177], v[50:53]
	v_mfma_f32_16x16x32_bf16 v[46:49], v[134:137], v[186:189], v[46:49]
	v_mfma_f32_16x16x32_bf16 v[42:45], v[142:145], v[186:189], v[42:45]
	v_mfma_f32_16x16x32_bf16 v[38:41], v[134:137], v[190:193], v[38:41]
	v_mfma_f32_16x16x32_bf16 v[34:37], v[142:145], v[190:193], v[34:37]
	v_mfma_f32_16x16x32_bf16 v[30:33], v[146:149], v[162:165], v[30:33]
	v_mfma_f32_16x16x32_bf16 v[26:29], v[154:157], v[162:165], v[26:29]
	v_mfma_f32_16x16x32_bf16 v[22:25], v[146:149], v[166:169], v[22:25]
	v_mfma_f32_16x16x32_bf16 v[18:21], v[154:157], v[166:169], v[18:21]
	v_mfma_f32_16x16x32_bf16 v[14:17], v[146:149], v[178:181], v[14:17]
	v_mfma_f32_16x16x32_bf16 v[10:13], v[154:157], v[178:181], v[10:13]
	v_mfma_f32_16x16x32_bf16 v[6:9], v[146:149], v[182:185], v[6:9]
	v_mfma_f32_16x16x32_bf16 v[2:5], v[154:157], v[182:185], v[2:5]
	v_mfma_f32_16x16x32_bf16 v[30:33], v[150:153], v[170:173], v[30:33]
	v_mfma_f32_16x16x32_bf16 v[26:29], v[158:161], v[170:173], v[26:29]
	v_mfma_f32_16x16x32_bf16 v[22:25], v[150:153], v[174:177], v[22:25]
	v_mfma_f32_16x16x32_bf16 v[18:21], v[158:161], v[174:177], v[18:21]
	v_mfma_f32_16x16x32_bf16 v[14:17], v[150:153], v[186:189], v[14:17]
	v_mfma_f32_16x16x32_bf16 v[10:13], v[158:161], v[186:189], v[10:13]
	v_mfma_f32_16x16x32_bf16 v[6:9], v[150:153], v[190:193], v[6:9]
	v_mfma_f32_16x16x32_bf16 v[2:5], v[158:161], v[190:193], v[2:5]
	s_barrier
	s_setprio 0
	s_add_i32 s33, s33, 2
	s_addk_i32 s53, 0x100
	s_cmp_gt_u32 s33, 13
	s_cbranch_scc0 .LBB0_1122
	s_and_b64 vcc, exec, s[16:17]
	s_cbranch_vccz .LBB0_1125
	s_barrier

.LBB0_1251:
	ds_read_b128 v[130:133], v239
	ds_read_b128 v[134:137], v240
	ds_read_b128 v[138:141], v241
	ds_read_b128 v[142:145], v242
	ds_read_b128 v[146:149], v243
	ds_read_b128 v[150:153], v244
	ds_read_b128 v[154:157], v245
	ds_read_b128 v[158:161], v246
	s_add_i32 s8, s51, s5
	s_add_i32 s31, s46, s5
	s_add_i32 s30, s8, 0x2000
	s_addk_i32 s31, 0x2000
	s_cmp_eq_u32 s5, 0
	s_cselect_b32 s33, s0, s30
	s_cselect_b32 s31, s1, s31
	s_add_i32 s30, s33, 0x80
	s_add_i32 s34, s8, 0x101f80
	s_mov_b32 s8, s70
	s_mov_b32 m0, s61
	ds_read_b128 v[162:165], v247
	ds_read_b128 v[166:169], v247 offset:2048
	ds_read_b128 v[170:173], v248
	ds_read_b128 v[174:177], v248 offset:2048
	ds_read_b128 v[178:181], v247 offset:4096
	ds_read_b128 v[182:185], v247 offset:6144
	ds_read_b128 v[186:189], v248 offset:4096
	ds_read_b128 v[190:193], v248 offset:6144
	buffer_load_dwordx4 v230, s[8:11], s34 offen lds
	s_mov_b32 m0, s64
	s_nop 0
	buffer_load_dwordx4 v233, s[8:11], s34 offen lds
	s_waitcnt vmcnt(8)
	s_waitcnt lgkmcnt(0)
	s_setprio 1
	v_mfma_f32_16x16x32_bf16 v[74:77], v[130:133], v[162:165], v[74:77]
	v_mfma_f32_16x16x32_bf16 v[70:73], v[138:141], v[162:165], v[70:73]
	v_mfma_f32_16x16x32_bf16 v[66:69], v[130:133], v[166:169], v[66:69]
	v_mfma_f32_16x16x32_bf16 v[82:85], v[138:141], v[166:169], v[82:85]
	s_barrier
	v_mfma_f32_16x16x32_bf16 v[78:81], v[130:133], v[178:181], v[78:81]
	v_mfma_f32_16x16x32_bf16 v[90:93], v[138:141], v[178:181], v[90:93]
	v_mfma_f32_16x16x32_bf16 v[86:89], v[130:133], v[182:185], v[86:89]
	v_mfma_f32_16x16x32_bf16 v[102:105], v[138:141], v[182:185], v[102:105]
	v_mfma_f32_16x16x32_bf16 v[74:77], v[134:137], v[170:173], v[74:77]
	v_mfma_f32_16x16x32_bf16 v[70:73], v[142:145], v[170:173], v[70:73]
	v_mfma_f32_16x16x32_bf16 v[66:69], v[134:137], v[174:177], v[66:69]
	v_mfma_f32_16x16x32_bf16 v[82:85], v[142:145], v[174:177], v[82:85]
	v_mfma_f32_16x16x32_bf16 v[78:81], v[134:137], v[186:189], v[78:81]
	v_mfma_f32_16x16x32_bf16 v[90:93], v[142:145], v[186:189], v[90:93]
	v_mfma_f32_16x16x32_bf16 v[86:89], v[134:137], v[190:193], v[86:89]
	v_mfma_f32_16x16x32_bf16 v[102:105], v[142:145], v[190:193], v[102:105]
	v_mfma_f32_16x16x32_bf16 v[98:101], v[146:149], v[162:165], v[98:101]
	v_mfma_f32_16x16x32_bf16 v[94:97], v[154:157], v[162:165], v[94:97]
	v_mfma_f32_16x16x32_bf16 v[106:109], v[146:149], v[166:169], v[106:109]
	v_mfma_f32_16x16x32_bf16 v[110:113], v[154:157], v[166:169], v[110:113]
	v_mfma_f32_16x16x32_bf16 v[114:117], v[146:149], v[178:181], v[114:117]
	v_mfma_f32_16x16x32_bf16 v[118:121], v[154:157], v[178:181], v[118:121]
	v_mfma_f32_16x16x32_bf16 v[122:125], v[146:149], v[182:185], v[122:125]
	v_mfma_f32_16x16x32_bf16 v[126:129], v[154:157], v[182:185], v[126:129]
	v_mfma_f32_16x16x32_bf16 v[98:101], v[150:153], v[170:173], v[98:101]
	v_mfma_f32_16x16x32_bf16 v[94:97], v[158:161], v[170:173], v[94:97]
	v_mfma_f32_16x16x32_bf16 v[106:109], v[150:153], v[174:177], v[106:109]
	v_mfma_f32_16x16x32_bf16 v[110:113], v[158:161], v[174:177], v[110:113]
	v_mfma_f32_16x16x32_bf16 v[114:117], v[150:153], v[186:189], v[114:117]
	v_mfma_f32_16x16x32_bf16 v[118:121], v[158:161], v[186:189], v[118:121]
	v_mfma_f32_16x16x32_bf16 v[122:125], v[150:153], v[190:193], v[122:125]
	v_mfma_f32_16x16x32_bf16 v[126:129], v[158:161], v[190:193], v[126:129]
	s_barrier
	s_setprio 0
	s_mov_b32 m0, s43
	ds_read_b128 v[162:165], v247 offset:16384
	ds_read_b128 v[166:169], v247 offset:18432
	ds_read_b128 v[170:173], v248 offset:16384
	ds_read_b128 v[174:177], v248 offset:18432
	ds_read_b128 v[178:181], v247 offset:20480
	ds_read_b128 v[182:185], v247 offset:22528
	ds_read_b128 v[186:189], v248 offset:20480
	ds_read_b128 v[190:193], v248 offset:22528
	buffer_load_dwordx4 v231, s[8:11], s31 offen lds
	s_mov_b32 m0, s44
	s_add_i32 s34, s31, 0x100000
	buffer_load_dwordx4 v234, s[8:11], s31 offen lds
	s_mov_b32 m0, s45
	s_nop 0
	buffer_load_dwordx4 v231, s[8:11], s34 offen lds
	s_mov_b32 m0, s47
	s_nop 0
	buffer_load_dwordx4 v234, s[8:11], s34 offen lds
	s_mov_b32 m0, s42
	s_nop 0
	buffer_load_dwordx4 v230, s[8:11], s33 offen lds
	s_mov_b32 m0, s48
	s_nop 0
	buffer_load_dwordx4 v233, s[8:11], s33 offen lds
	s_waitcnt vmcnt(8)
	s_waitcnt lgkmcnt(0)
	s_setprio 1
	v_mfma_f32_16x16x32_bf16 v[10:13], v[130:133], v[162:165], v[10:13]
	v_mfma_f32_16x16x32_bf16 v[6:9], v[138:141], v[162:165], v[6:9]
	s_barrier
	v_mfma_f32_16x16x32_bf16 v[0:3], v[130:133], v[166:169], v[2:5]
	v_mfma_f32_16x16x32_bf16 v[18:21], v[138:141], v[166:169], v[18:21]
	v_mfma_f32_16x16x32_bf16 v[14:17], v[130:133], v[178:181], v[14:17]
	v_mfma_f32_16x16x32_bf16 v[26:29], v[138:141], v[178:181], v[26:29]
	v_mfma_f32_16x16x32_bf16 v[22:25], v[130:133], v[182:185], v[22:25]
	v_mfma_f32_16x16x32_bf16 v[38:41], v[138:141], v[182:185], v[38:41]
	v_mfma_f32_16x16x32_bf16 v[10:13], v[134:137], v[170:173], v[10:13]
	v_mfma_f32_16x16x32_bf16 v[6:9], v[142:145], v[170:173], v[6:9]
	v_mfma_f32_16x16x32_bf16 v[0:3], v[134:137], v[174:177], v[0:3]
	v_mfma_f32_16x16x32_bf16 v[18:21], v[142:145], v[174:177], v[18:21]
	v_mfma_f32_16x16x32_bf16 v[14:17], v[134:137], v[186:189], v[14:17]
	v_mfma_f32_16x16x32_bf16 v[26:29], v[142:145], v[186:189], v[26:29]
	v_mfma_f32_16x16x32_bf16 v[22:25], v[134:137], v[190:193], v[22:25]
	v_mfma_f32_16x16x32_bf16 v[38:41], v[142:145], v[190:193], v[38:41]
	v_mfma_f32_16x16x32_bf16 v[34:37], v[146:149], v[162:165], v[34:37]
	v_mfma_f32_16x16x32_bf16 v[30:33], v[154:157], v[162:165], v[30:33]
	v_mfma_f32_16x16x32_bf16 v[42:45], v[146:149], v[166:169], v[42:45]
	v_mfma_f32_16x16x32_bf16 v[46:49], v[154:157], v[166:169], v[46:49]
	v_mfma_f32_16x16x32_bf16 v[50:53], v[146:149], v[178:181], v[50:53]
	v_mfma_f32_16x16x32_bf16 v[54:57], v[154:157], v[178:181], v[54:57]
	v_mfma_f32_16x16x32_bf16 v[58:61], v[146:149], v[182:185], v[58:61]
	v_mfma_f32_16x16x32_bf16 v[62:65], v[154:157], v[182:185], v[62:65]
	v_mfma_f32_16x16x32_bf16 v[34:37], v[150:153], v[170:173], v[34:37]
	v_mfma_f32_16x16x32_bf16 v[30:33], v[158:161], v[170:173], v[30:33]
	v_mfma_f32_16x16x32_bf16 v[42:45], v[150:153], v[174:177], v[42:45]
	v_mfma_f32_16x16x32_bf16 v[46:49], v[158:161], v[174:177], v[46:49]
	v_mfma_f32_16x16x32_bf16 v[50:53], v[150:153], v[186:189], v[50:53]
	v_mfma_f32_16x16x32_bf16 v[54:57], v[158:161], v[186:189], v[54:57]
	v_mfma_f32_16x16x32_bf16 v[58:61], v[150:153], v[190:193], v[58:61]
	v_mfma_f32_16x16x32_bf16 v[62:65], v[158:161], v[190:193], v[62:65]
	s_barrier
	s_setprio 0
	ds_read_b128 v[130:133], v194
	ds_read_b128 v[134:137], v195
	ds_read_b128 v[138:141], v196
	ds_read_b128 v[142:145], v197
	ds_read_b128 v[146:149], v198
	ds_read_b128 v[150:153], v199
	ds_read_b128 v[154:157], v200
	ds_read_b128 v[158:161], v201
	s_add_i32 s33, s33, 0x100000
	s_mov_b32 m0, s49
	ds_read_b128 v[162:165], v247 offset:32768
	ds_read_b128 v[166:169], v247 offset:34816
	ds_read_b128 v[170:173], v248 offset:32768
	ds_read_b128 v[174:177], v248 offset:34816
	ds_read_b128 v[178:181], v247 offset:36864
	ds_read_b128 v[182:185], v247 offset:38912
	ds_read_b128 v[186:189], v248 offset:36864
	ds_read_b128 v[190:193], v248 offset:38912
	buffer_load_dwordx4 v230, s[8:11], s33 offen lds
	s_mov_b32 m0, s50
	s_nop 0
	buffer_load_dwordx4 v233, s[8:11], s33 offen lds
	s_waitcnt vmcnt(8)
	s_waitcnt lgkmcnt(0)
	s_setprio 1
	v_mfma_f32_16x16x32_bf16 v[74:77], v[130:133], v[162:165], v[74:77]
	v_mfma_f32_16x16x32_bf16 v[70:73], v[138:141], v[162:165], v[70:73]
	v_mfma_f32_16x16x32_bf16 v[66:69], v[130:133], v[166:169], v[66:69]
	v_mfma_f32_16x16x32_bf16 v[82:85], v[138:141], v[166:169], v[82:85]
	s_barrier
	v_mfma_f32_16x16x32_bf16 v[78:81], v[130:133], v[178:181], v[78:81]
	v_mfma_f32_16x16x32_bf16 v[90:93], v[138:141], v[178:181], v[90:93]
	v_mfma_f32_16x16x32_bf16 v[86:89], v[130:133], v[182:185], v[86:89]
	v_mfma_f32_16x16x32_bf16 v[102:105], v[138:141], v[182:185], v[102:105]
	v_mfma_f32_16x16x32_bf16 v[74:77], v[134:137], v[170:173], v[74:77]
	v_mfma_f32_16x16x32_bf16 v[70:73], v[142:145], v[170:173], v[70:73]
	v_mfma_f32_16x16x32_bf16 v[66:69], v[134:137], v[174:177], v[66:69]
	v_mfma_f32_16x16x32_bf16 v[82:85], v[142:145], v[174:177], v[82:85]
	v_mfma_f32_16x16x32_bf16 v[78:81], v[134:137], v[186:189], v[78:81]
	v_mfma_f32_16x16x32_bf16 v[90:93], v[142:145], v[186:189], v[90:93]
	v_mfma_f32_16x16x32_bf16 v[86:89], v[134:137], v[190:193], v[86:89]
	v_mfma_f32_16x16x32_bf16 v[102:105], v[142:145], v[190:193], v[102:105]
	v_mfma_f32_16x16x32_bf16 v[98:101], v[146:149], v[162:165], v[98:101]
	v_mfma_f32_16x16x32_bf16 v[94:97], v[154:157], v[162:165], v[94:97]
	v_mfma_f32_16x16x32_bf16 v[106:109], v[146:149], v[166:169], v[106:109]
	v_mfma_f32_16x16x32_bf16 v[110:113], v[154:157], v[166:169], v[110:113]
	v_mfma_f32_16x16x32_bf16 v[114:117], v[146:149], v[178:181], v[114:117]
	v_mfma_f32_16x16x32_bf16 v[118:121], v[154:157], v[178:181], v[118:121]
	v_mfma_f32_16x16x32_bf16 v[122:125], v[146:149], v[182:185], v[122:125]
	v_mfma_f32_16x16x32_bf16 v[126:129], v[154:157], v[182:185], v[126:129]
	v_mfma_f32_16x16x32_bf16 v[98:101], v[150:153], v[170:173], v[98:101]
	v_mfma_f32_16x16x32_bf16 v[94:97], v[158:161], v[170:173], v[94:97]
	v_mfma_f32_16x16x32_bf16 v[106:109], v[150:153], v[174:177], v[106:109]
	v_mfma_f32_16x16x32_bf16 v[110:113], v[158:161], v[174:177], v[110:113]
	v_mfma_f32_16x16x32_bf16 v[114:117], v[150:153], v[186:189], v[114:117]
	v_mfma_f32_16x16x32_bf16 v[118:121], v[158:161], v[186:189], v[118:121]
	v_mfma_f32_16x16x32_bf16 v[122:125], v[150:153], v[190:193], v[122:125]
	v_mfma_f32_16x16x32_bf16 v[126:129], v[158:161], v[190:193], v[126:129]
	s_barrier
	s_setprio 0
	s_mov_b32 m0, s53
	s_add_i32 s33, s31, 0x80
	ds_read_b128 v[162:165], v247 offset:49152
	ds_read_b128 v[166:169], v247 offset:51200
	ds_read_b128 v[170:173], v248 offset:49152
	ds_read_b128 v[174:177], v248 offset:51200
	ds_read_b128 v[178:181], v247 offset:53248
	ds_read_b128 v[182:185], v247 offset:55296
	ds_read_b128 v[186:189], v248 offset:53248
	ds_read_b128 v[190:193], v248 offset:55296
	buffer_load_dwordx4 v231, s[8:11], s33 offen lds
	s_mov_b32 m0, s54
	s_add_i32 s31, s31, 0x100080
	buffer_load_dwordx4 v234, s[8:11], s33 offen lds
	s_mov_b32 m0, s57
	s_nop 0
	buffer_load_dwordx4 v231, s[8:11], s31 offen lds
	s_mov_b32 m0, s58
	s_nop 0
	buffer_load_dwordx4 v234, s[8:11], s31 offen lds
	s_mov_b32 m0, s55
	s_nop 0
	buffer_load_dwordx4 v230, s[8:11], s30 offen lds
	s_mov_b32 m0, s56
	s_nop 0
	buffer_load_dwordx4 v233, s[8:11], s30 offen lds
	s_waitcnt vmcnt(8)
	s_waitcnt lgkmcnt(0)
	s_setprio 1
	v_mfma_f32_16x16x32_bf16 v[10:13], v[130:133], v[162:165], v[10:13]
	v_mfma_f32_16x16x32_bf16 v[4:7], v[138:141], v[162:165], v[6:9]
	s_barrier
	v_mfma_f32_16x16x32_bf16 v[0:3], v[130:133], v[166:169], v[0:3]
	v_mfma_f32_16x16x32_bf16 v[18:21], v[138:141], v[166:169], v[18:21]
	v_mfma_f32_16x16x32_bf16 v[14:17], v[130:133], v[178:181], v[14:17]
	v_mfma_f32_16x16x32_bf16 v[26:29], v[138:141], v[178:181], v[26:29]
	v_mfma_f32_16x16x32_bf16 v[22:25], v[130:133], v[182:185], v[22:25]
	v_mfma_f32_16x16x32_bf16 v[38:41], v[138:141], v[182:185], v[38:41]
	v_mfma_f32_16x16x32_bf16 v[10:13], v[134:137], v[170:173], v[10:13]
	v_mfma_f32_16x16x32_bf16 v[6:9], v[142:145], v[170:173], v[4:7]
	v_mfma_f32_16x16x32_bf16 v[2:5], v[134:137], v[174:177], v[0:3]
	v_mfma_f32_16x16x32_bf16 v[18:21], v[142:145], v[174:177], v[18:21]
	v_mfma_f32_16x16x32_bf16 v[14:17], v[134:137], v[186:189], v[14:17]
	v_mfma_f32_16x16x32_bf16 v[26:29], v[142:145], v[186:189], v[26:29]
	v_mfma_f32_16x16x32_bf16 v[22:25], v[134:137], v[190:193], v[22:25]
	v_mfma_f32_16x16x32_bf16 v[38:41], v[142:145], v[190:193], v[38:41]
	v_mfma_f32_16x16x32_bf16 v[34:37], v[146:149], v[162:165], v[34:37]
	v_mfma_f32_16x16x32_bf16 v[30:33], v[154:157], v[162:165], v[30:33]
	v_mfma_f32_16x16x32_bf16 v[42:45], v[146:149], v[166:169], v[42:45]
	v_mfma_f32_16x16x32_bf16 v[46:49], v[154:157], v[166:169], v[46:49]
	v_mfma_f32_16x16x32_bf16 v[50:53], v[146:149], v[178:181], v[50:53]
	v_mfma_f32_16x16x32_bf16 v[54:57], v[154:157], v[178:181], v[54:57]
	v_mfma_f32_16x16x32_bf16 v[58:61], v[146:149], v[182:185], v[58:61]
	v_mfma_f32_16x16x32_bf16 v[62:65], v[154:157], v[182:185], v[62:65]
	v_mfma_f32_16x16x32_bf16 v[34:37], v[150:153], v[170:173], v[34:37]
	v_mfma_f32_16x16x32_bf16 v[30:33], v[158:161], v[170:173], v[30:33]
	v_mfma_f32_16x16x32_bf16 v[42:45], v[150:153], v[174:177], v[42:45]
	v_mfma_f32_16x16x32_bf16 v[46:49], v[158:161], v[174:177], v[46:49]
	v_mfma_f32_16x16x32_bf16 v[50:53], v[150:153], v[186:189], v[50:53]
	v_mfma_f32_16x16x32_bf16 v[54:57], v[158:161], v[186:189], v[54:57]
	v_mfma_f32_16x16x32_bf16 v[58:61], v[150:153], v[190:193], v[58:61]
	v_mfma_f32_16x16x32_bf16 v[62:65], v[158:161], v[190:193], v[62:65]
	s_barrier
	s_setprio 0
	s_add_i32 s4, s4, 2
	s_addk_i32 s5, 0x100
	s_cmp_gt_u32 s4, 61
	s_cbranch_scc0 .LBB0_1251
	s_and_b64 vcc, exec, s[18:19]
	s_cbranch_vccz .LBB0_1254
	s_barrier
